# attn items remapped XCD-contiguous; conv sample/prompt mix per XCD; entry cg grid.sync removed
# speedup vs baseline: 1.0060x; 1.0060x over previous
; #define PH(k) if (lo <= (k) && (k) < hi) for (int rep_ = 0; rep_ <= ((REP_MASK >> (k)) & 1); ++rep_)
; #define SEAM(k) if (lo <= (k) && (k) + 1 < hi) grid_bar(barctr, (unsigned)((k) + 1 - lo) * gridDim.x, wave)
; __device__ void phase_prep(const Params& p, float* lds, int wave) {
;     const int total = N_FILT_ITEMS + N_MOD_ITEMS + N_TR_ITEMS;
;     float colsum[16];
; #pragma unroll
;     for (int i = 0; i < 16; ++i) colsum[i] = 0.f;
;     for (int it = blockIdx.x; it < total; it += gridDim.x) {
; __global__ void __launch_bounds__(NTHR, 2) fwd_kernel(Params p) {
;     extern __shared__ __attribute__((aligned(16))) unsigned char smem[];
;     cg::grid_group grid = cg::this_grid();
;     const int lo = p.ph_lo, hi = p.ph_hi;
;     const int wave = __builtin_amdgcn_readfirstlane(threadIdx.x >> 6);
;     unsigned* barctr = (unsigned*)(p.ws + WS_BAR);
;     if (hi - lo > 1) grid.sync();
;     unsigned char* ws = p.ws;
;     const float* mod = (const float*)(ws + WS_MOD);
;     bf16_t* hbuf = (bf16_t*)(ws + WS_RA);
;     ...
;     PH(0) { phase_prep(p, (float*)smem, wave); } SEAM(0);
_Z10fwd_kernel6Params:
	s_load_dwordx8 s[4:11], s[0:1], 0xc0
	s_load_dword s93, s[0:1], 0xf8
	s_add_u32 s62, s0, 0xf8
	s_addc_u32 s63, s1, 0
	v_and_b32_e32 v1, 0x3ff, v0
	s_waitcnt lgkmcnt(0)
	v_writelane_b32 v253, s4, 0
	s_movk_i32 s3, 0x3ff
	v_readfirstlane_b32 s74, v1
	v_writelane_b32 v253, s5, 1
	v_writelane_b32 v253, s6, 2
	v_writelane_b32 v253, s7, 3
	v_writelane_b32 v253, s8, 4
	v_writelane_b32 v253, s9, 5
	v_writelane_b32 v253, s10, 6
	v_writelane_b32 v253, s11, 7
	s_load_dwordx4 s[4:7], s[0:1], 0xe0
	s_load_dwordx2 s[72:73], s[0:1], 0xf0
	s_waitcnt lgkmcnt(0)
	v_writelane_b32 v253, s4, 8
	s_nop 1
	v_writelane_b32 v253, s5, 9
	v_writelane_b32 v253, s6, 10
	v_writelane_b32 v253, s7, 11
	s_sub_i32 s4, s73, s72
	s_cmp_lt_i32 s4, 2
.LBB0_12:
	s_load_dwordx16 s[4:19], s[0:1], 0x0
	s_and_b32 s70, s74, 0xffffffc0
	s_cmp_lt_i32 s72, 1
	s_cselect_b64 s[94:95], -1, 0
	s_cmp_gt_i32 s72, 0
	s_waitcnt lgkmcnt(0)
	v_writelane_b32 v253, s4, 12
	s_nop 1
	v_writelane_b32 v253, s5, 13
	v_writelane_b32 v253, s6, 14
	v_writelane_b32 v253, s7, 15
	v_writelane_b32 v253, s8, 16
	v_writelane_b32 v253, s9, 17
	v_writelane_b32 v253, s10, 18
	v_writelane_b32 v253, s11, 19
	v_writelane_b32 v253, s12, 20
	v_writelane_b32 v253, s13, 21
	v_writelane_b32 v253, s14, 22
	v_writelane_b32 v253, s15, 23
	v_writelane_b32 v253, s16, 24
	v_writelane_b32 v253, s17, 25
	v_writelane_b32 v253, s18, 26
	v_writelane_b32 v253, s19, 27
	s_load_dwordx16 s[4:19], s[0:1], 0x40
	s_waitcnt lgkmcnt(0)
	v_writelane_b32 v253, s4, 28
	s_nop 1
	v_writelane_b32 v253, s5, 29
	v_writelane_b32 v253, s6, 30
	v_writelane_b32 v253, s7, 31
	v_writelane_b32 v253, s8, 32
	v_writelane_b32 v253, s9, 33
	v_writelane_b32 v253, s10, 34
	v_writelane_b32 v253, s11, 35
	v_writelane_b32 v253, s12, 36
	v_writelane_b32 v253, s13, 37
	v_writelane_b32 v253, s14, 38
	v_writelane_b32 v253, s15, 39
	v_writelane_b32 v253, s16, 40
	v_writelane_b32 v253, s17, 41
	v_writelane_b32 v253, s18, 42
	v_writelane_b32 v253, s19, 43
	s_load_dwordx16 s[4:19], s[0:1], 0x80
	s_cselect_b64 s[0:1], -1, 0
	s_cmp_lt_i32 s73, 1
	s_waitcnt lgkmcnt(0)
	v_writelane_b32 v253, s4, 44
	s_nop 1
	v_writelane_b32 v253, s5, 45
	v_writelane_b32 v253, s6, 46
	v_writelane_b32 v253, s7, 47
	v_writelane_b32 v253, s8, 48
	v_writelane_b32 v253, s9, 49
	v_writelane_b32 v253, s10, 50
	v_writelane_b32 v253, s11, 51
	v_writelane_b32 v253, s12, 52
	v_writelane_b32 v253, s13, 53
	v_writelane_b32 v253, s14, 54
	v_writelane_b32 v253, s15, 55
	v_writelane_b32 v253, s16, 56
	v_writelane_b32 v253, s17, 57
	v_writelane_b32 v253, s18, 58
	v_writelane_b32 v253, s19, 59
	s_cselect_b64 s[4:5], -1, 0
	s_or_b64 s[0:1], s[0:1], s[4:5]
	s_and_b64 vcc, exec, s[0:1]
	v_writelane_b32 v253, s70, 60
	s_cbranch_vccnz .LBB0_138
	s_cmpk_gt_i32 s2, 0x111f
	s_cbranch_scc1 .LBB0_138
	v_readlane_b32 s4, v253, 8
	v_readlane_b32 s6, v253, 10
	v_readlane_b32 s7, v253, 11
	s_add_u32 s96, s6, 0x1500000
	s_addc_u32 s97, s7, 0
	s_add_u32 s64, s6, 0xa00000
	s_addc_u32 s65, s7, 0
	s_add_u32 s66, s6, 0x800000
	s_addc_u32 s67, s7, 0
	s_add_u32 s68, s6, 0x200000
	s_addc_u32 s69, s7, 0
	s_add_u32 s40, s6, 0x10000
	v_mbcnt_lo_u32_b32 v0, -1, 0
	s_addc_u32 s41, s7, 0
	v_mov_b32_e32 v1, 0
	s_mov_b32 s25, 0
	s_movk_i32 s33, 0x104
	s_movk_i32 s75, 0x2c00
	s_movk_i32 s92, 0x3000
	s_movk_i32 s42, 0x1ff
	s_movk_i32 s43, 0x90
	s_movk_i32 s44, 0x3fff
	s_movk_i32 s45, 0x6000
	s_mov_b64 s[26:27], 0x6000
	v_mov_b32_e32 v40, 0x38d1b717
	v_mov_b32_e32 v41, 0xbf1f24be
	v_mov_b32_e32 v42, 0x3e642e9d
	s_movk_i32 s46, 0x1f8
	s_movk_i32 s47, 0x1000
	s_add_i32 s48, 0, 0x900
	s_brev_b32 s49, 18
	s_mov_b32 s50, 0xfe5163ab
	s_mov_b32 s51, 0x3c439041
	s_mov_b32 s52, 0xdb629599
	s_mov_b32 s53, 0xf534ddc0
	s_mov_b32 s54, 0xfc2757d1
	s_mov_b32 s55, 0x4e441529
	s_mov_b32 s56, 0xa2f9836e
	s_mov_b32 s57, 0x3fc90fda
	s_mov_b32 s58, 0x3f22f983
	s_mov_b32 s59, 0xbfc90fda
	v_mov_b32_e32 v43, 0x3c0881c4
	v_mov_b32_e32 v44, 0xbab64f3b
	s_add_i32 s60, 0, 0x1900
	v_mov_b32_e32 v45, 0x7fc00000
	v_not_b32_e32 v46, 63
	v_not_b32_e32 v47, 31
	v_mbcnt_hi_u32_b32 v48, -1, v0
	v_mov_b32_e32 v49, 0
	v_mov_b32_e32 v50, 0
	v_mov_b32_e32 v51, 0
	v_mov_b32_e32 v52, 0
	v_mov_b32_e32 v53, 0
	v_mov_b32_e32 v54, 0
	v_mov_b32_e32 v55, 0
	v_mov_b32_e32 v56, 0
	v_mov_b32_e32 v57, 0
	v_mov_b32_e32 v58, 0
	v_mov_b32_e32 v59, 0
	v_mov_b32_e32 v60, 0
	v_mov_b32_e32 v61, 0
	v_mov_b32_e32 v62, 0
	v_mov_b32_e32 v63, 0
	v_mov_b32_e32 v64, 0
	s_mov_b32 s61, s2
	v_readlane_b32 s5, v253, 9
	s_branch .LBB0_17

; __device__ __forceinline__ void phase_conv(const Params& p, int o, unsigned char* smem, int wave) {
;     ...
;     const bool g256 = gridDim.x == 256;
;     const int nrounds = g256 ? 4 : (1024 + gridDim.x - 1) / gridDim.x;
; #pragma unroll 1
;     for (int rd = 0; rd < nrounds; ++rd) {
;         bool samp; int c;
;         if (g256) { samp = ((blockIdx.x + rd) & 1) == 0; c = (rd >> 1) * 256 + blockIdx.x; }
;         else { const int it = blockIdx.x + rd * gridDim.x; if (it >= 1024) break; samp = it < 512; c = it & 511; }
;         const int lsel = samp ? 1 : 0; const int L = samp ? TS : TP;
.LBB0_220:
	s_lshr_b32 s3, s2, 3
	s_add_i32 s3, s6, s3
	s_bitcmp0_b32 s3, 0
	s_cselect_b64 s[70:71], -1, 0
	s_lshl_b32 s3, s6, 7
	s_and_b32 s3, s3, 0x7fffff00
	s_add_i32 s50, s3, s2
	s_mov_b64 s[52:53], -1

; __device__ void phase_attn(const Params& p, unsigned char* smem, int wave) {
;     const int tid = fresh_tid(wave), ht = tid, w4 = tid >> 6, lane = tid & 63, ql = lane & 15, gq = lane >> 4;
;     bf16_t* Qs = (bf16_t*)smem; bf16_t* Ks = Qs + 128 * ATT_LD; bf16_t* Vs = Ks + 256 * ATT_LD;
;     const bf16_t* qkv = (const bf16_t*)(p.ws + WS_RC);
;     float* lse = (float*)(p.ws + WS_LSE);
;     const int npairs = 15360;
;     u32x4 qr[2], kr[4], vr[4];
;     ...
;     if ((int)blockIdx.x < npairs) { ATT_DECODE(blockIdx.x) ATT_LOAD(); }
.LBB0_708:
	s_cmp_lt_i32 s72, 6
	s_cselect_b64 s[36:37], -1, 0
	s_cmp_gt_i32 s72, 5
	s_cselect_b64 s[0:1], -1, 0
	s_cmp_lt_i32 s73, 6
	s_cselect_b64 s[4:5], -1, 0
	s_or_b64 s[0:1], s[0:1], s[4:5]
	v_readlane_b32 s66, v254, 1
	s_and_b64 vcc, exec, s[0:1]
	v_readlane_b32 s64, v254, 3
	v_readlane_b32 s67, v254, 2
	s_cbranch_vccnz .LBB0_734
	s_and_b32 s99, s2, 7
	s_lshl_b32 s99, s99, 5
	s_lshr_b32 s0, s2, 3
	s_or_b32 s99, s99, s0
	s_cmpk_lg_i32 s93, 0x100
	s_cselect_b32 s99, s2, s99
	s_cmpk_lt_i32 s2, 0x3c00
	v_mbcnt_lo_u32_b32 v44, -1, 0
	v_mbcnt_hi_u32_b32 v44, -1, v44
	s_cbranch_scc0 .LBB0_734
	v_readlane_b32 s4, v253, 8
	v_readlane_b32 s6, v253, 10
	v_readlane_b32 s7, v253, 11
	s_add_u32 s38, s6, 0x1b00000
	s_mul_hi_i32 s0, s99, 0x66666667
	s_addc_u32 s39, s7, 0
	s_lshr_b32 s1, s0, 31
	s_ashr_i32 s0, s0, 8
	s_add_i32 s0, s0, s1
	s_mul_i32 s1, s0, 0x280
	s_sub_i32 s1, s99, s1
	v_readlane_b32 s5, v253, 9
	s_lshl_b32 s4, s1, 7
	s_and_b32 s3, s0, -8
	s_and_b32 s5, s4, 0xfffff800
	s_and_b32 s6, s1, 15
	s_add_i32 s7, s1, 0xfffffe00
	s_cmp_eq_u32 s3, 8
	s_cselect_b32 s3, 2, 4
	s_cselect_b32 s8, 3, 15
	s_cmp_lt_u32 s0, 8
	s_cselect_b32 s4, 0, s3
	s_cselect_b32 s3, 0, s8
	s_cmpk_lt_i32 s1, 0x200
	s_cselect_b32 s1, s6, s7
	s_movk_i32 s6, 0x800
	s_cselect_b32 s5, s5, 0x10000
	s_cselect_b32 s6, s6, 0x4000
	s_and_b32 s3, s3, s1
	s_lshr_b32 s1, s1, s4
	s_lshl_b32 s0, s0, 6
	s_waitcnt vmcnt(0)
	v_mbcnt_lo_u32_b32 v0, -1, 0
	v_mbcnt_hi_u32_b32 v0, -1, v0
	s_lshl_b32 s1, s1, 7
	v_or_b32_e32 v36, s70, v0
	s_and_b32 s0, s0, 0x1c0
	v_lshlrev_b32_e32 v0, 3, v0
	v_ashrrev_i32_e32 v9, 3, v36
	v_and_or_b32 v45, v0, 56, s0
	v_add_u32_e32 v0, s1, v9
	s_or_b32 s5, s3, s5
	v_lshlrev_b32_e32 v0, s4, v0
	v_add_u32_e32 v0, s5, v0
	s_movk_i32 s3, 0x600
	v_mul_lo_u32 v0, v0, s3
	v_mov_b32_e32 v8, 0
	v_or_b32_e32 v0, v0, v45
	v_mov_b32_e32 v1, v8
	v_lshl_add_u64 v[10:11], v[0:1], 1, s[38:39]
	v_add_u32_e32 v0, 0x200, v36
	v_ashrrev_i32_e32 v12, 3, v0
	v_add_u32_e32 v0, s1, v12
	v_lshlrev_b32_e32 v0, s4, v0
	v_add_u32_e32 v0, s5, v0
	v_mul_lo_u32 v0, v0, s3
	v_or_b32_e32 v0, v0, v45
	v_lshl_add_u64 v[14:15], v[0:1], 1, s[38:39]
	global_load_dwordx4 v[0:3], v[10:11], off
	global_load_dwordx4 v[4:7], v[14:15], off
	s_sub_i32 s7, s1, 64
	s_lshr_b32 s6, s6, s4
	v_add_u32_e32 v13, s7, v9
	v_mov_b32_e32 v10, v8
	v_mov_b32_e32 v11, v8
	v_cmp_lt_i32_e32 vcc, -1, v13
	v_cmp_gt_i32_e64 s[0:1], s6, v13
	v_mov_b32_e32 v9, v8
	v_mov_b64_e32 v[18:19], v[10:11]
	v_mov_b64_e32 v[22:23], v[10:11]
	s_and_b64 s[8:9], vcc, s[0:1]
	v_mov_b64_e32 v[16:17], v[8:9]
	v_mov_b64_e32 v[20:21], v[8:9]
	s_and_saveexec_b64 s[0:1], s[8:9]
	s_cbranch_execz .LBB0_712
	v_lshlrev_b32_e32 v13, s4, v13
	v_add_u32_e32 v13, s5, v13
	v_mul_lo_u32 v13, v13, s3
	v_or_b32_e32 v14, v13, v45
	v_mov_b32_e32 v15, v8
	v_lshl_add_u64 v[14:15], v[14:15], 1, s[38:39]
	global_load_dwordx4 v[16:19], v[14:15], off offset:1024
	global_load_dwordx4 v[20:23], v[14:15], off offset:2048

; __device__ void phase_attn(const Params& p, unsigned char* smem, int wave) {
;     ...
;     for (int pr = blockIdx.x; pr < npairs; pr += gridDim.x) {
;         ATT_DECODE(pr)
;         bf16_t* ato = (bf16_t*)(p.ws + (br < 2 ? WS_RA + br * ATO_STRIDE_01 : WS_ATO2));
;         __syncthreads();
;         const int hs = fresh_tid(wave);
; #pragma unroll
;         for (int c_ = 0; c_ < 2; ++c_) { const int e = hs + 512 * c_; *(u32x4*)(Qs + (e >> 3) * ATT_LD + (e & 7) * 8) = qr[c_]; }
; #pragma unroll
;         for (int c_ = 0; c_ < 4; ++c_) { const int e = hs + 512 * c_; *(u32x4*)(Ks + (e >> 3) * ATT_LD + (e & 7) * 8) = kr[c_]; *(u32x4*)(Vs + (e >> 3) * ATT_LD + (e & 7) * 8) = vr[c_]; }
;         __syncthreads();
;         if (pr + (int)gridDim.x < npairs) { ATT_DECODE(pr + gridDim.x) ATT_LOAD(); }
;         const bf16x8 qf0 = *(const bf16x8*)(Qs + (16 * w4 + ql) * ATT_LD + gq * 8), qf1 = *(const bf16x8*)(Qs + (16 * w4 + ql) * ATT_LD + 32 + gq * 8);
;         f32x4 sc[10];
; #pragma unroll
;         for (int kt = 0; kt < 9; ++kt) { const bf16_t* kr = Ks + (16 * w4 + 16 * kt + ql) * ATT_LD + gq * 8;
;             f32x4 a = (f32x4){0.f, 0.f, 0.f, 0.f};
;             a = __builtin_amdgcn_mfma_f32_16x16x32_bf16(*(const bf16x8*)kr, qf0, a, 0, 0, 0);
;             a = __builtin_amdgcn_mfma_f32_16x16x32_bf16(*(const bf16x8*)(kr + 32), qf1, a, 0, 0, 0);
;             sc[kt] = a; if (kt % 3 == 2) __builtin_amdgcn_sched_barrier(0); }
;         const float slope = exp2f(-(float)(h + 1)) * (float)d * 1.4426950408889634f;
;         const int qi = i0 + 16 * w4 + ql;
;         float mx = -1e30f;
; #pragma unroll
;         for (int kt = 0; kt < 9; ++kt)
; #pragma unroll
;             for (int j = 0; j < 4; ++j) { const int rel = 16 * kt + 4 * gq + j - 64 - ql; const int jk = qi + rel;
;                 const bool relok = (kt == 0) ? (rel >= -64) : ((kt == 8) ? (rel <= 64) : true);
;                 const bool ok = relok && ((unsigned)jk < (unsigned)Ls);
;                 const float v = ok ? sc[kt][j] * 0.18033688011112042f - slope * fabsf((float)rel) : -1e30f;
;                 sc[kt][j] = v; mx = fmaxf(mx, v); }
.LBB0_718:
	s_or_b64 exec, exec, s[0:1]
	v_or_b32_e32 v12, s64, v44
	v_bfe_u32 v13, v44, 4, 2
	v_and_b32_e32 v66, 15, v44
	v_ashrrev_i32_e32 v12, 2, v12
	v_lshlrev_b32_e32 v141, 2, v13
	v_and_b32_e32 v67, -16, v12
	v_bfi_b32 v12, -16, v12, v44
	s_movk_i32 s33, 0x90
	v_sub_u32_e32 v142, v141, v66
	v_mul_lo_u32 v12, v12, s33
	v_lshl_add_u32 v14, v13, 4, 0
	v_subrev_u32_e32 v143, 64, v142
	v_subrev_u32_e32 v144, 63, v142
	v_add_u32_e32 v140, v14, v12
	v_bfe_u32 v12, v44, 2, 2
	v_lshlrev_b32_e32 v14, 3, v44
	v_cmp_eq_u32_e64 s[0:1], 0, v13
	v_cvt_f32_i32_e32 v13, v143
	v_cvt_f32_i32_e32 v44, v144
	v_subrev_u32_e32 v145, 62, v142
	v_subrev_u32_e32 v146, 61, v142
	v_and_b32_e32 v69, 0x7fffffff, v13
	v_and_b32_e32 v71, 0x7fffffff, v44
	v_cvt_f32_i32_e32 v13, v145
	v_cvt_f32_i32_e32 v44, v146
	v_subrev_u32_e32 v147, 48, v142
	v_subrev_u32_e32 v148, 47, v142
	v_subrev_u32_e32 v149, 46, v142
	v_subrev_u32_e32 v150, 45, v142
	v_and_b32_e32 v73, 0x7fffffff, v13
	v_and_b32_e32 v75, 0x7fffffff, v44
	v_cvt_f32_i32_e32 v13, v147
	v_cvt_f32_i32_e32 v44, v148
	v_cvt_f32_i32_e32 v45, v149
	v_cvt_f32_i32_e32 v46, v150
	v_subrev_u32_e32 v151, 32, v142
	v_subrev_u32_e32 v152, 31, v142
	v_subrev_u32_e32 v153, 30, v142
	v_subrev_u32_e32 v154, 29, v142
	v_and_b32_e32 v77, 0x7fffffff, v13
	v_and_b32_e32 v79, 0x7fffffff, v44
	v_and_b32_e32 v81, 0x7fffffff, v45
	v_and_b32_e32 v83, 0x7fffffff, v46
	v_cvt_f32_i32_e32 v13, v151
	v_cvt_f32_i32_e32 v44, v152
	v_cvt_f32_i32_e32 v45, v153
	v_cvt_f32_i32_e32 v46, v154
	v_add_u32_e32 v155, -16, v142
	v_add_u32_e32 v156, -15, v142
	v_add_u32_e32 v157, -14, v142
	v_add_u32_e32 v158, -13, v142
	v_and_b32_e32 v85, 0x7fffffff, v13
	v_and_b32_e32 v87, 0x7fffffff, v44
	v_and_b32_e32 v89, 0x7fffffff, v45
	v_and_b32_e32 v91, 0x7fffffff, v46
	v_cvt_f32_i32_e32 v13, v155
	v_cvt_f32_i32_e32 v44, v156
	v_cvt_f32_i32_e32 v45, v157
	v_cvt_f32_i32_e32 v46, v158
	v_add_u32_e32 v159, 1, v142
	v_add_u32_e32 v160, 2, v142
	v_add_u32_e32 v161, 3, v142
	v_and_b32_e32 v93, 0x7fffffff, v13
	v_and_b32_e32 v95, 0x7fffffff, v44
	v_and_b32_e32 v97, 0x7fffffff, v45
	v_and_b32_e32 v99, 0x7fffffff, v46
	v_cvt_f32_i32_e32 v13, v142
	v_cvt_f32_i32_e32 v44, v159
	v_cvt_f32_i32_e32 v45, v160
	v_cvt_f32_i32_e32 v46, v161
	v_add_u32_e32 v162, 16, v142
	v_add_u32_e32 v163, 17, v142
	v_add_u32_e32 v164, 18, v142
	v_add_u32_e32 v165, 19, v142
	v_add_u32_e32 v166, 32, v142
	v_add_u32_e32 v167, 33, v142
	v_add_u32_e32 v168, 34, v142
	v_add_u32_e32 v169, 35, v142
	v_add_u32_e32 v170, 48, v142
	v_add_u32_e32 v171, 49, v142
	v_add_u32_e32 v172, 50, v142
	v_add_u32_e32 v173, 51, v142
	v_add_u32_e32 v174, 64, v142
	v_add_u32_e32 v175, 0x41, v142
	v_add_u32_e32 v176, 0x42, v142
	v_add_u32_e32 v177, 0x43, v142
	v_readlane_b32 s4, v253, 8
	v_or3_b32 v12, v12, v141, v67
	v_cvt_f32_u32_e32 v109, v162
	v_cvt_f32_u32_e32 v111, v163
	v_cvt_f32_u32_e32 v113, v164
	v_cvt_f32_u32_e32 v115, v165
	v_cvt_f32_u32_e32 v117, v166
	v_cvt_f32_u32_e32 v119, v167
	v_cvt_f32_u32_e32 v121, v168
	v_cvt_f32_u32_e32 v123, v169
	v_cvt_f32_u32_e32 v125, v170
	v_cvt_f32_u32_e32 v127, v171
	v_cvt_f32_u32_e32 v129, v172
	v_cvt_f32_u32_e32 v131, v173
	v_cvt_f32_u32_e32 v133, v174
	v_cvt_f32_u32_e32 v135, v175
	v_cvt_f32_u32_e32 v137, v176
	v_cvt_f32_u32_e32 v178, v177
	v_readlane_b32 s6, v253, 10
	v_and_b32_e32 v14, 24, v14
	v_mul_lo_u32 v12, v12, s33
	v_readlane_b32 s5, v253, 9
	v_readlane_b32 s7, v253, 11
	s_add_u32 s40, s6, 0x2eb00000
	v_add3_u32 v179, 0, v14, v12
	s_mov_b32 s44, 0x3e38aa3b
	v_mov_b32_e32 v136, 0x3e38aa3b
	v_mbcnt_lo_u32_b32 v12, -1, 0
	s_addc_u32 s41, s7, 0
	s_mov_b32 s43, 0
	v_cmp_lt_i32_e64 s[24:25], -1, v142
	v_cmp_lt_i32_e64 s[4:5], -2, v142
	v_cmp_lt_i32_e64 s[6:7], -3, v142
	v_cmp_lt_i32_e64 s[8:9], -4, v142
	v_and_b32_e32 v101, 0x7fffffff, v13
	v_and_b32_e32 v103, 0x7fffffff, v44
	v_and_b32_e32 v105, 0x7fffffff, v45
	v_and_b32_e32 v107, 0x7fffffff, v46
	v_cmp_gt_i32_e64 s[10:11], 1, v142
	v_cmp_gt_i32_e64 s[12:13], 0, v142
	v_cmp_gt_i32_e64 s[14:15], -1, v142
	v_cmp_gt_i32_e64 s[16:17], -2, v142
	v_add_u32_e32 v180, 0xd800, v179
	s_mov_b32 s45, 0x3fb8aa3b
	v_mov_b32_e32 v134, v136
	v_mov_b32_e32 v132, v136
	v_mov_b32_e32 v130, v136
	v_mov_b32_e32 v128, v136
	v_mov_b32_e32 v126, v136
	v_mov_b32_e32 v124, v136
	v_mov_b32_e32 v122, v136
	v_mov_b32_e32 v120, v136
	v_mov_b32_e32 v118, v136
	v_mov_b32_e32 v116, v136
	v_mov_b32_e32 v114, v136
	v_mov_b32_e32 v112, v136
	v_mov_b32_e32 v110, v136
	v_mov_b32_e32 v108, v136
	v_mov_b32_e32 v106, v136
	v_mov_b32_e32 v104, v136
	v_mov_b32_e32 v102, v136
	v_mov_b32_e32 v100, v136
	v_mov_b32_e32 v98, v136
	v_mov_b32_e32 v96, v136
	v_mov_b32_e32 v94, v136
	v_mov_b32_e32 v92, v136
	v_mov_b32_e32 v90, v136
	v_mov_b32_e32 v88, v136
	v_mov_b32_e32 v86, v136
	v_mov_b32_e32 v84, v136
	v_mov_b32_e32 v82, v136
	v_mov_b32_e32 v80, v136
	v_mov_b32_e32 v78, v136
	v_mov_b32_e32 v76, v136
	v_mov_b32_e32 v74, v136
	v_mov_b32_e32 v72, v136
	v_mov_b32_e32 v70, v136
	v_mov_b32_e32 v68, v136
	s_lshl_b32 s48, s99, 7
	s_lshl_b32 s49, s93, 7
	s_movk_i32 s50, 0x800
	s_mov_b32 s51, 0x42fc0000
	s_mov_b32 s52, 0xf149f2ca
	v_lshlrev_b32_e32 v138, 1, v66
	s_mov_b32 s53, 0x800000
	s_mov_b32 s54, 0x3f317217
	s_mov_b32 s55, 0x7f800000
	v_mov_b32_e32 v44, 0
	v_mov_b32_e32 v181, 0x42800000
	v_mov_b32_e32 v182, 0xf149f2ca
	v_mbcnt_hi_u32_b32 v183, -1, v12
	v_mov_b32_e32 v184, 0x41b17218
	v_mov_b32_e32 v185, 0x14000
	s_mov_b32 s23, s99
	s_branch .LBB0_720

; __global__ void __launch_bounds__(NTHR, 2) fwd_kernel(Params p) {
;     extern __shared__ __attribute__((aligned(16))) unsigned char smem[];
;     cg::grid_group grid = cg::this_grid();
;     const int lo = p.ph_lo, hi = p.ph_hi;
;     const int wave = __builtin_amdgcn_readfirstlane(threadIdx.x >> 6);
	.amdhsa_kernel _Z10fwd_kernel6Params
		.amdhsa_group_segment_fixed_size 0
		.amdhsa_private_segment_fixed_size 0
		.amdhsa_kernarg_size 504
		.amdhsa_user_sgpr_count 2
		.amdhsa_user_sgpr_dispatch_ptr 0
		.amdhsa_user_sgpr_queue_ptr 0
		.amdhsa_user_sgpr_kernarg_segment_ptr 1
		.amdhsa_user_sgpr_dispatch_id 0
		.amdhsa_user_sgpr_kernarg_preload_length 0
		.amdhsa_user_sgpr_kernarg_preload_offset 0
		.amdhsa_user_sgpr_private_segment_size 0
		.amdhsa_uses_dynamic_stack 0
		.amdhsa_enable_private_segment 0
		.amdhsa_system_sgpr_workgroup_id_x 1
		.amdhsa_system_sgpr_workgroup_id_y 0
		.amdhsa_system_sgpr_workgroup_id_z 0
		.amdhsa_system_sgpr_workgroup_info 0
		.amdhsa_system_vgpr_workitem_id 2
		.amdhsa_next_free_vgpr 255
		.amdhsa_next_free_sgpr 100
		.amdhsa_accum_offset 256
		.amdhsa_reserve_vcc 1
		.amdhsa_float_round_mode_32 0
		.amdhsa_float_round_mode_16_64 0
		.amdhsa_float_denorm_mode_32 3
		.amdhsa_float_denorm_mode_16_64 3
		.amdhsa_dx10_clamp 1
		.amdhsa_ieee_mode 1
		.amdhsa_fp16_overflow 0
		.amdhsa_tg_split 0
		.amdhsa_exception_fp_ieee_invalid_op 0
		.amdhsa_exception_fp_denorm_src 0
		.amdhsa_exception_fp_ieee_div_zero 0
		.amdhsa_exception_fp_ieee_overflow 0
		.amdhsa_exception_fp_ieee_underflow 0
		.amdhsa_exception_fp_ieee_inexact 0
		.amdhsa_exception_int_div_zero 0
	.end_amdhsa_kernel

; __global__ void __launch_bounds__(NTHR, 2) fwd_kernel(Params p) {
;     extern __shared__ __attribute__((aligned(16))) unsigned char smem[];
;     cg::grid_group grid = cg::this_grid();
;     const int lo = p.ph_lo, hi = p.ph_hi;
;     const int wave = __builtin_amdgcn_readfirstlane(threadIdx.x >> 6);
amdhsa.kernels:
  - .agpr_count:     0
    .args:
      - .offset:         0
        .size:           248
        .value_kind:     by_value
      - .offset:         248
        .size:           4
        .value_kind:     hidden_block_count_x
      - .offset:         252
        .size:           4
        .value_kind:     hidden_block_count_y
      - .offset:         256
        .size:           4
        .value_kind:     hidden_block_count_z
      - .offset:         260
        .size:           2
        .value_kind:     hidden_group_size_x
      - .offset:         262
        .size:           2
        .value_kind:     hidden_group_size_y
      - .offset:         264
        .size:           2
        .value_kind:     hidden_group_size_z
      - .offset:         266
        .size:           2
        .value_kind:     hidden_remainder_x
      - .offset:         268
        .size:           2
        .value_kind:     hidden_remainder_y
      - .offset:         270
        .size:           2
        .value_kind:     hidden_remainder_z
      - .offset:         288
        .size:           8
        .value_kind:     hidden_global_offset_x
      - .offset:         296
        .size:           8
        .value_kind:     hidden_global_offset_y
      - .offset:         304
        .size:           8
        .value_kind:     hidden_global_offset_z
      - .offset:         312
        .size:           2
        .value_kind:     hidden_grid_dims
      - .offset:         336
        .size:           8
        .value_kind:     hidden_multigrid_sync_arg
      - .offset:         368
        .size:           4
        .value_kind:     hidden_dynamic_lds_size
    .group_segment_fixed_size: 0
    .kernarg_segment_align: 8
    .kernarg_segment_size: 504
    .language:       OpenCL C
    .language_version:
      - 2
      - 0
    .max_flat_workgroup_size: 512
    .name:           _Z10fwd_kernel6Params
    .private_segment_fixed_size: 0
    .sgpr_count:     106
    .sgpr_spill_count: 139
    .symbol:         _Z10fwd_kernel6Params.kd
    .uniform_work_group_size: 1
    .uses_dynamic_stack: false
    .vgpr_count:     255
    .vgpr_spill_count: 0
    .wavefront_size: 64
